# attention tile loop: per-tile barrier moved from the head of sub-step 1 softmax (16 exps right after release) into the P.V MFMA run (MFMA-first head after release)
# speedup vs baseline: 1.0110x; 1.0110x over previous
; __device__ __forceinline__ unsigned pk2(float lo, float hi) { return pg8::cvt_pk_bf16(lo, hi); }
; #define MFMA32(a, b, c) __builtin_amdgcn_mfma_f32_32x32x16_bf16((a), (b), (c), 0, 0, 0)
; __device__ __forceinline__ void attn_phase(const Args& a, int l, bool with_ctx, unsigned char* lds) {
;     ...
;                 for (int r = 0; r < 16; ++r) { S[r] = __builtin_amdgcn_exp2f(S[r]); ps += S[r]; }
;                 lrun += ps;
;                 u32x4 p0, p1;
;                 p0.x = pk2(S[0], S[1]); p0.y = pk2(S[2], S[3]); p0.z = pk2(S[4], S[5]); p0.w = pk2(S[6], S[7]);
;                 p1.x = pk2(S[8], S[9]); p1.y = pk2(S[10], S[11]); p1.z = pk2(S[12], S[13]); p1.w = pk2(S[14], S[15]);
;                 const bf16x8 pa0 = __builtin_bit_cast(bf16x8, p0), pa1 = __builtin_bit_cast(bf16x8, p1);
; #pragma unroll
;                 for (int j = 0; j < 4; ++j) O[j] = MFMA32(vf[2 * j], pa0, O[j]);
; #pragma unroll
;                 for (int j = 0; j < 4; ++j) O[j] = MFMA32(vf[2 * j + 1], pa1, O[j]);
;             }
;             if (t + 1 < nt) { unsigned char* kd = kdst + (cur ^ 1) * BUF; unsigned char* vd = vdst + (cur ^ 1) * BUF;
;                 *(u32x4*)kd = k0; *(u32x4*)(kd + 9216) = k1; *(u32x4*)vd = v0; *(u32x4*)(vd + 9216) = v1; }
;             __syncthreads();
.LBB0_412:
	v_exp_f32_e32 v67, v68
	v_exp_f32_e32 v68, v69
	v_exp_f32_e32 v69, v70
	v_exp_f32_e32 v70, v71
	v_exp_f32_e32 v71, v72
	v_exp_f32_e32 v72, v73
	v_exp_f32_e32 v73, v74
	v_exp_f32_e32 v74, v75
	v_cvt_pk_bf16_f32 v184, v67, v68
	v_cvt_pk_bf16_f32 v185, v69, v70
	v_cvt_pk_bf16_f32 v186, v71, v72
	v_cvt_pk_bf16_f32 v187, v73, v74
	v_exp_f32_e32 v75, v76
	v_exp_f32_e32 v76, v77
	s_waitcnt lgkmcnt(11)
	v_mfma_f32_32x32x16_bf16 v[50:65], v[136:139], v[184:187], v[50:65]
	v_exp_f32_e32 v77, v78
	v_exp_f32_e32 v78, v79
	v_exp_f32_e32 v79, v80
	v_exp_f32_e32 v80, v81
	v_exp_f32_e32 v81, v82
	v_exp_f32_e32 v82, v83
	v_cvt_pk_bf16_f32 v214, v75, v76
	s_waitcnt lgkmcnt(9)
	v_mfma_f32_32x32x16_bf16 v[34:49], v[140:143], v[184:187], v[34:49]
	v_cvt_pk_bf16_f32 v215, v77, v78
	v_cvt_pk_bf16_f32 v216, v79, v80
	v_cvt_pk_bf16_f32 v217, v81, v82
	s_andn2_b64 vcc, exec, s[10:11]
	s_waitcnt lgkmcnt(7)
	v_mfma_f32_32x32x16_bf16 v[18:33], v[144:147], v[184:187], v[18:33]
	s_waitcnt lgkmcnt(5)
	v_mfma_f32_32x32x16_bf16 v[2:17], v[132:135], v[184:187], v[2:17]
	s_waitcnt lgkmcnt(0)
	s_barrier
	v_mfma_f32_32x32x16_bf16 v[50:65], v[116:119], v[214:217], v[50:65]
	v_mfma_f32_32x32x16_bf16 v[34:49], v[120:123], v[214:217], v[34:49]
	v_mfma_f32_32x32x16_bf16 v[18:33], v[124:127], v[214:217], v[18:33]
	s_waitcnt lgkmcnt(4)
	v_mfma_f32_32x32x16_bf16 v[2:17], v[128:131], v[214:217], v[2:17]
